# v41 + GLA log-sigmoid: removed provably dead denormal-scaling and isfinite selects around v_log_f32 (argument is in [1,2]), 16 sites
# speedup vs baseline: 1.0132x; 1.0011x over previous
; DEVI void gla_seq(const Params& p, int l, int item, char* lds) {
;     ...
;     {
;       float run = 0.f;
; #pragma unroll
;       for (int ii = 0; ii < 16; ++ii) {
;         const float* gr_ = gas + (seg * 16 + ii) * 16;
;         float z = ba;
; #pragma unroll
;         for (int r = 0; r < 16; ++r) z += gr_[r] * w2[r];
;         const float ls = fminf(z, 0.f) - __logf(1.f + __expf(-fabsf(z)));
;         run += ls * (1.f / 16.f);
;         bcum[ii] = run;
;       }
;       segtot[seg * 128 + d] = run;
;     }
;     __syncthreads();
.LBB0_399:
	ds_read_b128 v[16:19], v127
	ds_read_b128 v[20:23], v127 offset:16
	ds_read_b128 v[24:27], v127 offset:32
	ds_read_b128 v[28:31], v127 offset:48
	s_mov_b32 s29, 0x3f317217
	s_waitcnt lgkmcnt(3)
	v_fma_f32 v16, v106, v16, v122
	v_fmac_f32_e32 v16, v107, v17
	v_fmac_f32_e32 v16, v108, v18
	v_fmac_f32_e32 v16, v109, v19
	s_waitcnt lgkmcnt(2)
	v_fmac_f32_e32 v16, v110, v20
	v_fmac_f32_e32 v16, v111, v21
	v_fmac_f32_e32 v16, v112, v22
	v_fmac_f32_e32 v16, v113, v23
	s_waitcnt lgkmcnt(1)
	v_fmac_f32_e32 v16, v114, v24
	v_fmac_f32_e32 v16, v115, v25
	v_fmac_f32_e32 v16, v116, v26
	v_fmac_f32_e32 v16, v117, v27
	s_waitcnt lgkmcnt(0)
	v_fmac_f32_e32 v16, v118, v28
	v_fmac_f32_e32 v16, v119, v29
	v_fmac_f32_e32 v16, v120, v30
	v_fmac_f32_e32 v16, v121, v31
	v_min_f32_e32 v17, 0, v16
	v_mul_f32_e64 v16, |v16|, s54
	v_exp_f32_e32 v16, v16
	s_mov_b32 s27, 0x7f800000
	v_add_f32_e32 v16, 1.0, v16
	s_nop 1
	v_log_f32_e32 v16, v16
	s_nop 0
	v_mul_f32_e32 v18, 0x3f317217, v16
	v_fma_f32 v18, v16, s29, -v18
	v_fmac_f32_e32 v18, 0x3377d1cf, v16
	v_fmac_f32_e32 v18, 0x3f317217, v16
	s_nop 1
	v_sub_f32_e32 v16, v17, v18
	s_mov_b32 s2, 0x3d800000
	v_fma_f32 v20, v16, s2, 0
	ds_read_b128 v[16:19], v127 offset:64
	s_waitcnt lgkmcnt(0)
	v_fma_f32 v21, v106, v16, v122
	v_fmac_f32_e32 v21, v107, v17
	v_fmac_f32_e32 v21, v108, v18
	v_fmac_f32_e32 v21, v109, v19
	ds_read_b128 v[16:19], v127 offset:80
	s_waitcnt lgkmcnt(0)
	v_fmac_f32_e32 v21, v110, v16
	v_fmac_f32_e32 v21, v111, v17
	v_fmac_f32_e32 v21, v112, v18
	v_fmac_f32_e32 v21, v113, v19
	ds_read_b128 v[16:19], v127 offset:96
	s_waitcnt lgkmcnt(0)
	v_fmac_f32_e32 v21, v114, v16
	v_fmac_f32_e32 v21, v115, v17
	v_fmac_f32_e32 v21, v116, v18
	v_fmac_f32_e32 v21, v117, v19
	ds_read_b128 v[16:19], v127 offset:112
	s_waitcnt lgkmcnt(0)
	v_fmac_f32_e32 v21, v118, v16
	v_fmac_f32_e32 v21, v119, v17
	v_fmac_f32_e32 v21, v120, v18
	v_fmac_f32_e32 v21, v121, v19
	v_mul_f32_e64 v17, |v21|, s54
	v_exp_f32_e32 v17, v17
	v_min_f32_e32 v16, 0, v21
	v_add_f32_e32 v17, 1.0, v17
	s_nop 1
	v_log_f32_e32 v17, v17
	s_nop 0
	v_mul_f32_e32 v18, 0x3f317217, v17
	v_fma_f32 v18, v17, s29, -v18
	v_fmac_f32_e32 v18, 0x3377d1cf, v17
	v_fmac_f32_e32 v18, 0x3f317217, v17
	s_nop 1
	v_sub_f32_e32 v16, v16, v18
	v_fmamk_f32 v21, v16, 0x3d800000, v20
	ds_read_b128 v[16:19], v127 offset:128
	s_waitcnt lgkmcnt(0)
	v_fma_f32 v22, v106, v16, v122
	v_fmac_f32_e32 v22, v107, v17
	v_fmac_f32_e32 v22, v108, v18
	v_fmac_f32_e32 v22, v109, v19
	ds_read_b128 v[16:19], v127 offset:144
	s_waitcnt lgkmcnt(0)
	v_fmac_f32_e32 v22, v110, v16
	v_fmac_f32_e32 v22, v111, v17
	v_fmac_f32_e32 v22, v112, v18
	v_fmac_f32_e32 v22, v113, v19
	ds_read_b128 v[16:19], v127 offset:160
	s_waitcnt lgkmcnt(0)
	v_fmac_f32_e32 v22, v114, v16
	v_fmac_f32_e32 v22, v115, v17
	v_fmac_f32_e32 v22, v116, v18
	v_fmac_f32_e32 v22, v117, v19
	ds_read_b128 v[16:19], v127 offset:176
	s_waitcnt lgkmcnt(0)
	v_fmac_f32_e32 v22, v118, v16
	v_fmac_f32_e32 v22, v119, v17
	v_fmac_f32_e32 v22, v120, v18
	v_fmac_f32_e32 v22, v121, v19
	v_mul_f32_e64 v17, |v22|, s54
	v_exp_f32_e32 v17, v17
	v_min_f32_e32 v16, 0, v22
	v_add_f32_e32 v17, 1.0, v17
	s_nop 1
	v_log_f32_e32 v17, v17
	s_nop 0
	v_mul_f32_e32 v18, 0x3f317217, v17
	v_fma_f32 v18, v17, s29, -v18
	v_fmac_f32_e32 v18, 0x3377d1cf, v17
	v_fmac_f32_e32 v18, 0x3f317217, v17
	s_nop 1
	v_sub_f32_e32 v16, v16, v18
	v_fmamk_f32 v22, v16, 0x3d800000, v21
	ds_read_b128 v[16:19], v127 offset:192
	s_waitcnt lgkmcnt(0)
	v_fma_f32 v23, v106, v16, v122
	v_fmac_f32_e32 v23, v107, v17
	v_fmac_f32_e32 v23, v108, v18
	v_fmac_f32_e32 v23, v109, v19
	ds_read_b128 v[16:19], v127 offset:208
	s_waitcnt lgkmcnt(0)
	v_fmac_f32_e32 v23, v110, v16
	v_fmac_f32_e32 v23, v111, v17
	v_fmac_f32_e32 v23, v112, v18
	v_fmac_f32_e32 v23, v113, v19
	ds_read_b128 v[16:19], v127 offset:224
	s_waitcnt lgkmcnt(0)
	v_fmac_f32_e32 v23, v114, v16
	v_fmac_f32_e32 v23, v115, v17
	v_fmac_f32_e32 v23, v116, v18
	v_fmac_f32_e32 v23, v117, v19
	ds_read_b128 v[16:19], v127 offset:240
	s_waitcnt lgkmcnt(0)
	v_fmac_f32_e32 v23, v118, v16
	v_fmac_f32_e32 v23, v119, v17
	v_fmac_f32_e32 v23, v120, v18
	v_fmac_f32_e32 v23, v121, v19
	v_mul_f32_e64 v17, |v23|, s54
	v_exp_f32_e32 v17, v17
	v_min_f32_e32 v16, 0, v23
	v_add_f32_e32 v17, 1.0, v17
	s_nop 1
	v_log_f32_e32 v17, v17
	s_nop 0
	v_mul_f32_e32 v18, 0x3f317217, v17
	v_fma_f32 v18, v17, s29, -v18
	v_fmac_f32_e32 v18, 0x3377d1cf, v17
	v_fmac_f32_e32 v18, 0x3f317217, v17
	s_nop 1
	v_sub_f32_e32 v16, v16, v18
	v_fmamk_f32 v23, v16, 0x3d800000, v22
	ds_read_b128 v[16:19], v127 offset:256
	s_waitcnt lgkmcnt(0)
	v_fma_f32 v24, v106, v16, v122
	v_fmac_f32_e32 v24, v107, v17
	v_fmac_f32_e32 v24, v108, v18
	v_fmac_f32_e32 v24, v109, v19
	ds_read_b128 v[16:19], v127 offset:272
	s_waitcnt lgkmcnt(0)
	v_fmac_f32_e32 v24, v110, v16
	v_fmac_f32_e32 v24, v111, v17
	v_fmac_f32_e32 v24, v112, v18
	v_fmac_f32_e32 v24, v113, v19
	ds_read_b128 v[16:19], v127 offset:288
	s_waitcnt lgkmcnt(0)
	v_fmac_f32_e32 v24, v114, v16
	v_fmac_f32_e32 v24, v115, v17
	v_fmac_f32_e32 v24, v116, v18
	v_fmac_f32_e32 v24, v117, v19
	ds_read_b128 v[16:19], v127 offset:304
	s_waitcnt lgkmcnt(0)
	v_fmac_f32_e32 v24, v118, v16
	v_fmac_f32_e32 v24, v119, v17
	v_fmac_f32_e32 v24, v120, v18
	v_fmac_f32_e32 v24, v121, v19
	v_mul_f32_e64 v17, |v24|, s54
	v_exp_f32_e32 v17, v17
	v_min_f32_e32 v16, 0, v24
	v_add_f32_e32 v17, 1.0, v17
	s_nop 1
	v_log_f32_e32 v17, v17
	s_nop 0
	v_mul_f32_e32 v18, 0x3f317217, v17
	v_fma_f32 v18, v17, s29, -v18
	v_fmac_f32_e32 v18, 0x3377d1cf, v17
	v_fmac_f32_e32 v18, 0x3f317217, v17
	s_nop 1
	v_sub_f32_e32 v16, v16, v18
	v_fmamk_f32 v24, v16, 0x3d800000, v23
	ds_read_b128 v[16:19], v127 offset:320
	s_waitcnt lgkmcnt(0)
; DEVI void gla_seq(const Params& p, int l, int item, char* lds) {
;     ...
;     {
;       float run = 0.f;
; #pragma unroll
;       for (int ii = 0; ii < 16; ++ii) {
;         const float* gr_ = gas + (seg * 16 + ii) * 16;
;         float z = ba;
; #pragma unroll
;         for (int r = 0; r < 16; ++r) z += gr_[r] * w2[r];
;         const float ls = fminf(z, 0.f) - __logf(1.f + __expf(-fabsf(z)));
;         run += ls * (1.f / 16.f);
;         bcum[ii] = run;
;       }
;       segtot[seg * 128 + d] = run;
	v_fma_f32 v25, v106, v16, v122
	v_fmac_f32_e32 v25, v107, v17
	v_fmac_f32_e32 v25, v108, v18
	v_fmac_f32_e32 v25, v109, v19
	ds_read_b128 v[16:19], v127 offset:336
	s_waitcnt lgkmcnt(0)
	v_fmac_f32_e32 v25, v110, v16
	v_fmac_f32_e32 v25, v111, v17
	v_fmac_f32_e32 v25, v112, v18
	v_fmac_f32_e32 v25, v113, v19
	ds_read_b128 v[16:19], v127 offset:352
	s_waitcnt lgkmcnt(0)
	v_fmac_f32_e32 v25, v114, v16
	v_fmac_f32_e32 v25, v115, v17
	v_fmac_f32_e32 v25, v116, v18
	v_fmac_f32_e32 v25, v117, v19
	ds_read_b128 v[16:19], v127 offset:368
	s_waitcnt lgkmcnt(0)
	v_fmac_f32_e32 v25, v118, v16
	v_fmac_f32_e32 v25, v119, v17
	v_fmac_f32_e32 v25, v120, v18
	v_fmac_f32_e32 v25, v121, v19
	v_mul_f32_e64 v17, |v25|, s54
	v_exp_f32_e32 v17, v17
	v_min_f32_e32 v16, 0, v25
	v_add_f32_e32 v17, 1.0, v17
	s_nop 1
	v_log_f32_e32 v17, v17
	s_nop 0
	v_mul_f32_e32 v18, 0x3f317217, v17
	v_fma_f32 v18, v17, s29, -v18
	v_fmac_f32_e32 v18, 0x3377d1cf, v17
	v_fmac_f32_e32 v18, 0x3f317217, v17
	s_nop 1
	v_sub_f32_e32 v16, v16, v18
	v_fmamk_f32 v25, v16, 0x3d800000, v24
	ds_read_b128 v[16:19], v127 offset:384
	s_waitcnt lgkmcnt(0)
	v_fma_f32 v26, v106, v16, v122
	v_fmac_f32_e32 v26, v107, v17
	v_fmac_f32_e32 v26, v108, v18
	v_fmac_f32_e32 v26, v109, v19
	ds_read_b128 v[16:19], v127 offset:400
	s_waitcnt lgkmcnt(0)
	v_fmac_f32_e32 v26, v110, v16
	v_fmac_f32_e32 v26, v111, v17
	v_fmac_f32_e32 v26, v112, v18
	v_fmac_f32_e32 v26, v113, v19
	ds_read_b128 v[16:19], v127 offset:416
	s_waitcnt lgkmcnt(0)
	v_fmac_f32_e32 v26, v114, v16
	v_fmac_f32_e32 v26, v115, v17
	v_fmac_f32_e32 v26, v116, v18
	v_fmac_f32_e32 v26, v117, v19
	ds_read_b128 v[16:19], v127 offset:432
	s_waitcnt lgkmcnt(0)
	v_fmac_f32_e32 v26, v118, v16
	v_fmac_f32_e32 v26, v119, v17
	v_fmac_f32_e32 v26, v120, v18
	v_fmac_f32_e32 v26, v121, v19
	v_mul_f32_e64 v17, |v26|, s54
	v_exp_f32_e32 v17, v17
	v_min_f32_e32 v16, 0, v26
	v_add_f32_e32 v17, 1.0, v17
	s_nop 1
	v_log_f32_e32 v17, v17
	s_nop 0
	v_mul_f32_e32 v18, 0x3f317217, v17
	v_fma_f32 v18, v17, s29, -v18
	v_fmac_f32_e32 v18, 0x3377d1cf, v17
	v_fmac_f32_e32 v18, 0x3f317217, v17
	s_nop 1
	v_sub_f32_e32 v16, v16, v18
	v_fmamk_f32 v26, v16, 0x3d800000, v25
	ds_read_b128 v[16:19], v127 offset:448
	s_waitcnt lgkmcnt(0)
	v_fma_f32 v27, v106, v16, v122
	v_fmac_f32_e32 v27, v107, v17
	v_fmac_f32_e32 v27, v108, v18
	v_fmac_f32_e32 v27, v109, v19
	ds_read_b128 v[16:19], v127 offset:464
	s_waitcnt lgkmcnt(0)
	v_fmac_f32_e32 v27, v110, v16
	v_fmac_f32_e32 v27, v111, v17
	v_fmac_f32_e32 v27, v112, v18
	v_fmac_f32_e32 v27, v113, v19
	ds_read_b128 v[16:19], v127 offset:480
	s_waitcnt lgkmcnt(0)
	v_fmac_f32_e32 v27, v114, v16
	v_fmac_f32_e32 v27, v115, v17
	v_fmac_f32_e32 v27, v116, v18
	v_fmac_f32_e32 v27, v117, v19
	ds_read_b128 v[16:19], v127 offset:496
	s_waitcnt lgkmcnt(0)
	v_fmac_f32_e32 v27, v118, v16
	v_fmac_f32_e32 v27, v119, v17
	v_fmac_f32_e32 v27, v120, v18
	v_fmac_f32_e32 v27, v121, v19
	v_mul_f32_e64 v17, |v27|, s54
	v_exp_f32_e32 v17, v17
	v_min_f32_e32 v16, 0, v27
	v_add_f32_e32 v17, 1.0, v17
	s_nop 1
	v_log_f32_e32 v17, v17
	s_nop 0
	v_mul_f32_e32 v18, 0x3f317217, v17
	v_fma_f32 v18, v17, s29, -v18
	v_fmac_f32_e32 v18, 0x3377d1cf, v17
	v_fmac_f32_e32 v18, 0x3f317217, v17
	s_nop 1
	v_sub_f32_e32 v16, v16, v18
	v_fmamk_f32 v27, v16, 0x3d800000, v26
	ds_read_b128 v[16:19], v127 offset:512
	s_waitcnt lgkmcnt(0)
	v_fma_f32 v28, v106, v16, v122
	v_fmac_f32_e32 v28, v107, v17
	v_fmac_f32_e32 v28, v108, v18
	v_fmac_f32_e32 v28, v109, v19
	ds_read_b128 v[16:19], v127 offset:528
	s_waitcnt lgkmcnt(0)
	v_fmac_f32_e32 v28, v110, v16
	v_fmac_f32_e32 v28, v111, v17
	v_fmac_f32_e32 v28, v112, v18
	v_fmac_f32_e32 v28, v113, v19
	ds_read_b128 v[16:19], v127 offset:544
	s_waitcnt lgkmcnt(0)
	v_fmac_f32_e32 v28, v114, v16
	v_fmac_f32_e32 v28, v115, v17
	v_fmac_f32_e32 v28, v116, v18
	v_fmac_f32_e32 v28, v117, v19
	ds_read_b128 v[16:19], v127 offset:560
	s_waitcnt lgkmcnt(0)
	v_fmac_f32_e32 v28, v118, v16
	v_fmac_f32_e32 v28, v119, v17
	v_fmac_f32_e32 v28, v120, v18
	v_fmac_f32_e32 v28, v121, v19
	v_mul_f32_e64 v17, |v28|, s54
	v_exp_f32_e32 v17, v17
	v_min_f32_e32 v16, 0, v28
	v_add_f32_e32 v17, 1.0, v17
	s_nop 1
	v_log_f32_e32 v17, v17
	s_nop 0
	v_mul_f32_e32 v18, 0x3f317217, v17
	v_fma_f32 v18, v17, s29, -v18
	v_fmac_f32_e32 v18, 0x3377d1cf, v17
	v_fmac_f32_e32 v18, 0x3f317217, v17
	s_nop 1
	v_sub_f32_e32 v16, v16, v18
	v_fmamk_f32 v28, v16, 0x3d800000, v27
	ds_read_b128 v[16:19], v127 offset:576
	s_waitcnt lgkmcnt(0)
	v_fma_f32 v29, v106, v16, v122
	v_fmac_f32_e32 v29, v107, v17
	v_fmac_f32_e32 v29, v108, v18
	v_fmac_f32_e32 v29, v109, v19
	ds_read_b128 v[16:19], v127 offset:592
	s_waitcnt lgkmcnt(0)
	v_fmac_f32_e32 v29, v110, v16
	v_fmac_f32_e32 v29, v111, v17
	v_fmac_f32_e32 v29, v112, v18
	v_fmac_f32_e32 v29, v113, v19
	ds_read_b128 v[16:19], v127 offset:608
	s_waitcnt lgkmcnt(0)
	v_fmac_f32_e32 v29, v114, v16
	v_fmac_f32_e32 v29, v115, v17
	v_fmac_f32_e32 v29, v116, v18
	v_fmac_f32_e32 v29, v117, v19
	ds_read_b128 v[16:19], v127 offset:624
	s_waitcnt lgkmcnt(0)
	v_fmac_f32_e32 v29, v118, v16
	v_fmac_f32_e32 v29, v119, v17
	v_fmac_f32_e32 v29, v120, v18
	v_fmac_f32_e32 v29, v121, v19
	v_mul_f32_e64 v17, |v29|, s54
	v_exp_f32_e32 v17, v17
	v_min_f32_e32 v16, 0, v29
	v_add_f32_e32 v17, 1.0, v17
	s_nop 1
	v_log_f32_e32 v17, v17
	s_nop 0
	v_mul_f32_e32 v18, 0x3f317217, v17
	v_fma_f32 v18, v17, s29, -v18
	v_fmac_f32_e32 v18, 0x3377d1cf, v17
	v_fmac_f32_e32 v18, 0x3f317217, v17
	s_nop 1
	v_sub_f32_e32 v16, v16, v18
	v_fmamk_f32 v29, v16, 0x3d800000, v28
	ds_read_b128 v[16:19], v127 offset:640
	s_waitcnt lgkmcnt(0)
; DEVI void gla_seq(const Params& p, int l, int item, char* lds) {
;     ...
;     {
;       float run = 0.f;
; #pragma unroll
;       for (int ii = 0; ii < 16; ++ii) {
;         const float* gr_ = gas + (seg * 16 + ii) * 16;
;         float z = ba;
; #pragma unroll
;         for (int r = 0; r < 16; ++r) z += gr_[r] * w2[r];
;         const float ls = fminf(z, 0.f) - __logf(1.f + __expf(-fabsf(z)));
;         run += ls * (1.f / 16.f);
;         bcum[ii] = run;
;       }
;       segtot[seg * 128 + d] = run;
;     }
;     __syncthreads();
	v_fma_f32 v30, v106, v16, v122
	v_fmac_f32_e32 v30, v107, v17
	v_fmac_f32_e32 v30, v108, v18
	v_fmac_f32_e32 v30, v109, v19
	ds_read_b128 v[16:19], v127 offset:656
	s_waitcnt lgkmcnt(0)
	v_fmac_f32_e32 v30, v110, v16
	v_fmac_f32_e32 v30, v111, v17
	v_fmac_f32_e32 v30, v112, v18
	v_fmac_f32_e32 v30, v113, v19
	ds_read_b128 v[16:19], v127 offset:672
	s_waitcnt lgkmcnt(0)
	v_fmac_f32_e32 v30, v114, v16
	v_fmac_f32_e32 v30, v115, v17
	v_fmac_f32_e32 v30, v116, v18
	v_fmac_f32_e32 v30, v117, v19
	ds_read_b128 v[16:19], v127 offset:688
	s_waitcnt lgkmcnt(0)
	v_fmac_f32_e32 v30, v118, v16
	v_fmac_f32_e32 v30, v119, v17
	v_fmac_f32_e32 v30, v120, v18
	v_fmac_f32_e32 v30, v121, v19
	v_mul_f32_e64 v17, |v30|, s54
	v_exp_f32_e32 v17, v17
	v_min_f32_e32 v16, 0, v30
	v_add_f32_e32 v17, 1.0, v17
	s_nop 1
	v_log_f32_e32 v17, v17
	s_nop 0
	v_mul_f32_e32 v18, 0x3f317217, v17
	v_fma_f32 v18, v17, s29, -v18
	v_fmac_f32_e32 v18, 0x3377d1cf, v17
	v_fmac_f32_e32 v18, 0x3f317217, v17
	s_nop 1
	v_sub_f32_e32 v16, v16, v18
	v_fmamk_f32 v30, v16, 0x3d800000, v29
	ds_read_b128 v[16:19], v127 offset:704
	s_waitcnt lgkmcnt(0)
	v_fma_f32 v31, v106, v16, v122
	v_fmac_f32_e32 v31, v107, v17
	v_fmac_f32_e32 v31, v108, v18
	v_fmac_f32_e32 v31, v109, v19
	ds_read_b128 v[16:19], v127 offset:720
	s_waitcnt lgkmcnt(0)
	v_fmac_f32_e32 v31, v110, v16
	v_fmac_f32_e32 v31, v111, v17
	v_fmac_f32_e32 v31, v112, v18
	v_fmac_f32_e32 v31, v113, v19
	ds_read_b128 v[16:19], v127 offset:736
	s_waitcnt lgkmcnt(0)
	v_fmac_f32_e32 v31, v114, v16
	v_fmac_f32_e32 v31, v115, v17
	v_fmac_f32_e32 v31, v116, v18
	v_fmac_f32_e32 v31, v117, v19
	ds_read_b128 v[16:19], v127 offset:752
	s_waitcnt lgkmcnt(0)
	v_fmac_f32_e32 v31, v118, v16
	v_fmac_f32_e32 v31, v119, v17
	v_fmac_f32_e32 v31, v120, v18
	v_fmac_f32_e32 v31, v121, v19
	v_mul_f32_e64 v17, |v31|, s54
	v_exp_f32_e32 v17, v17
	v_min_f32_e32 v16, 0, v31
	v_add_f32_e32 v17, 1.0, v17
	s_nop 1
	v_log_f32_e32 v17, v17
	s_nop 0
	v_mul_f32_e32 v18, 0x3f317217, v17
	v_fma_f32 v18, v17, s29, -v18
	v_fmac_f32_e32 v18, 0x3377d1cf, v17
	v_fmac_f32_e32 v18, 0x3f317217, v17
	s_nop 1
	v_sub_f32_e32 v16, v16, v18
	v_fmamk_f32 v31, v16, 0x3d800000, v30
	ds_read_b128 v[16:19], v127 offset:768
	s_waitcnt lgkmcnt(0)
	v_fma_f32 v32, v106, v16, v122
	v_fmac_f32_e32 v32, v107, v17
	v_fmac_f32_e32 v32, v108, v18
	v_fmac_f32_e32 v32, v109, v19
	ds_read_b128 v[16:19], v127 offset:784
	s_waitcnt lgkmcnt(0)
	v_fmac_f32_e32 v32, v110, v16
	v_fmac_f32_e32 v32, v111, v17
	v_fmac_f32_e32 v32, v112, v18
	v_fmac_f32_e32 v32, v113, v19
	ds_read_b128 v[16:19], v127 offset:800
	s_waitcnt lgkmcnt(0)
	v_fmac_f32_e32 v32, v114, v16
	v_fmac_f32_e32 v32, v115, v17
	v_fmac_f32_e32 v32, v116, v18
	v_fmac_f32_e32 v32, v117, v19
	ds_read_b128 v[16:19], v127 offset:816
	s_waitcnt lgkmcnt(0)
	v_fmac_f32_e32 v32, v118, v16
	v_fmac_f32_e32 v32, v119, v17
	v_fmac_f32_e32 v32, v120, v18
	v_fmac_f32_e32 v32, v121, v19
	v_mul_f32_e64 v17, |v32|, s54
	v_exp_f32_e32 v17, v17
	v_min_f32_e32 v16, 0, v32
	v_add_f32_e32 v17, 1.0, v17
	s_nop 1
	v_log_f32_e32 v17, v17
	s_nop 0
	v_mul_f32_e32 v18, 0x3f317217, v17
	v_fma_f32 v18, v17, s29, -v18
	v_fmac_f32_e32 v18, 0x3377d1cf, v17
	v_fmac_f32_e32 v18, 0x3f317217, v17
	s_nop 1
	v_sub_f32_e32 v16, v16, v18
	v_fmamk_f32 v32, v16, 0x3d800000, v31
	ds_read_b128 v[16:19], v127 offset:832
	s_waitcnt lgkmcnt(0)
	v_fma_f32 v33, v106, v16, v122
	v_fmac_f32_e32 v33, v107, v17
	v_fmac_f32_e32 v33, v108, v18
	v_fmac_f32_e32 v33, v109, v19
	ds_read_b128 v[16:19], v127 offset:848
	s_waitcnt lgkmcnt(0)
	v_fmac_f32_e32 v33, v110, v16
	v_fmac_f32_e32 v33, v111, v17
	v_fmac_f32_e32 v33, v112, v18
	v_fmac_f32_e32 v33, v113, v19
	ds_read_b128 v[16:19], v127 offset:864
	s_waitcnt lgkmcnt(0)
	v_fmac_f32_e32 v33, v114, v16
	v_fmac_f32_e32 v33, v115, v17
	v_fmac_f32_e32 v33, v116, v18
	v_fmac_f32_e32 v33, v117, v19
	ds_read_b128 v[16:19], v127 offset:880
	s_waitcnt lgkmcnt(0)
	v_fmac_f32_e32 v33, v118, v16
	v_fmac_f32_e32 v33, v119, v17
	v_fmac_f32_e32 v33, v120, v18
	v_fmac_f32_e32 v33, v121, v19
	v_mul_f32_e64 v17, |v33|, s54
	v_exp_f32_e32 v17, v17
	v_min_f32_e32 v16, 0, v33
	v_add_f32_e32 v17, 1.0, v17
	s_nop 1
	v_log_f32_e32 v17, v17
	s_nop 0
	v_mul_f32_e32 v18, 0x3f317217, v17
	v_fma_f32 v18, v17, s29, -v18
	v_fmac_f32_e32 v18, 0x3377d1cf, v17
	v_fmac_f32_e32 v18, 0x3f317217, v17
	s_nop 1
	v_sub_f32_e32 v16, v16, v18
	v_fmamk_f32 v33, v16, 0x3d800000, v32
	ds_read_b128 v[16:19], v127 offset:896
	s_waitcnt lgkmcnt(0)
	v_fma_f32 v34, v106, v16, v122
	v_fmac_f32_e32 v34, v107, v17
	v_fmac_f32_e32 v34, v108, v18
	v_fmac_f32_e32 v34, v109, v19
	ds_read_b128 v[16:19], v127 offset:912
	s_waitcnt lgkmcnt(0)
	v_fmac_f32_e32 v34, v110, v16
	v_fmac_f32_e32 v34, v111, v17
	v_fmac_f32_e32 v34, v112, v18
	v_fmac_f32_e32 v34, v113, v19
	ds_read_b128 v[16:19], v127 offset:928
	s_waitcnt lgkmcnt(0)
	v_fmac_f32_e32 v34, v114, v16
	v_fmac_f32_e32 v34, v115, v17
	v_fmac_f32_e32 v34, v116, v18
	v_fmac_f32_e32 v34, v117, v19
	ds_read_b128 v[16:19], v127 offset:944
	s_waitcnt lgkmcnt(0)
	v_fmac_f32_e32 v34, v118, v16
	v_fmac_f32_e32 v34, v119, v17
	v_fmac_f32_e32 v34, v120, v18
	v_fmac_f32_e32 v34, v121, v19
	v_mul_f32_e64 v17, |v34|, s54
	v_exp_f32_e32 v17, v17
	v_min_f32_e32 v16, 0, v34
	v_add_f32_e32 v17, 1.0, v17
	s_nop 1
	v_log_f32_e32 v17, v17
	s_nop 0
	v_mul_f32_e32 v18, 0x3f317217, v17
	v_fma_f32 v18, v17, s29, -v18
	v_fmac_f32_e32 v18, 0x3377d1cf, v17
	v_fmac_f32_e32 v18, 0x3f317217, v17
	s_nop 1
	v_sub_f32_e32 v16, v16, v18
	v_fmamk_f32 v34, v16, 0x3d800000, v33
	ds_read_b128 v[16:19], v127 offset:960
	s_waitcnt lgkmcnt(0)
	v_fma_f32 v35, v106, v16, v122
	v_fmac_f32_e32 v35, v107, v17
	v_fmac_f32_e32 v35, v108, v18
	v_fmac_f32_e32 v35, v109, v19
	ds_read_b128 v[16:19], v127 offset:976
	s_waitcnt lgkmcnt(0)
	v_fmac_f32_e32 v35, v110, v16
	v_fmac_f32_e32 v35, v111, v17
	v_fmac_f32_e32 v35, v112, v18
	v_fmac_f32_e32 v35, v113, v19
	ds_read_b128 v[16:19], v127 offset:992
	s_waitcnt lgkmcnt(0)
	v_fmac_f32_e32 v35, v114, v16
	v_fmac_f32_e32 v35, v115, v17
	v_fmac_f32_e32 v35, v116, v18
	v_fmac_f32_e32 v35, v117, v19
	ds_read_b128 v[16:19], v127 offset:1008
	s_waitcnt lgkmcnt(0)
	v_fmac_f32_e32 v35, v118, v16
	v_fmac_f32_e32 v35, v119, v17
	v_fmac_f32_e32 v35, v120, v18
	v_fmac_f32_e32 v35, v121, v19
	v_mul_f32_e64 v17, |v35|, s54
	v_exp_f32_e32 v17, v17
	v_min_f32_e32 v16, 0, v35
	v_add_f32_e32 v17, 1.0, v17
	s_nop 1
	v_log_f32_e32 v17, v17
	s_nop 0
	v_mul_f32_e32 v18, 0x3f317217, v17
	v_fma_f32 v18, v17, s29, -v18
	v_fmac_f32_e32 v18, 0x3377d1cf, v17
	v_fmac_f32_e32 v18, 0x3f317217, v17
	s_nop 1
	v_sub_f32_e32 v16, v16, v18
	v_fmamk_f32 v35, v16, 0x3d800000, v34
	ds_write_b32 v128, v35
	s_waitcnt lgkmcnt(0)
	s_barrier
; DEVI u16 f2bf(float f) { return (u16)(cvtpk(f, 0.f) & 0xffffu); }
; DEVI float bf2f(u16 h) { return __uint_as_float(((unsigned)h) << 16); }
; DEVI void gla_seq(const Params& p, int l, int item, char* lds) {
;     ...
;     {
;       float pre = 0.f, tot = 0.f;
; #pragma unroll
;       for (int s_ = 0; s_ < 4; ++s_) { const float v = segtot[s_ * 128 + d]; tot += v; if (s_ < seg) pre += v; }
;       const float etot = __expf(tot);
;       if (seg == 0) ebl[d] = etot;
; #pragma unroll
;       for (int ii = 0; ii < 16; ++ii) {
;         const int i = seg * 16 + ii;
;         const float bb = bcum[ii] + pre;
;         const int so = i * 256 + (((d >> 3) ^ (i & 7)) << 4) + (d & 7) * 2;
;         const float q = bf2f(*(const u16*)(qs + so)), k = bf2f(*(const u16*)(ks + so));
;         const float eb = __expf(bb), ieb = __frcp_rn(eb);
;         *(u16*)(qs + so) = f2bf(q * eb);
;         *(u16*)(ks + so) = f2bf(k * ieb);
;         *(u16*)(kT + d * 144 + i * 2) = f2bf(k * (etot * ieb));
;       }
	ds_read2st64_b32 v[16:17], v129 offset1:2
	ds_read2st64_b32 v[18:19], v129 offset0:4 offset1:6
	s_waitcnt lgkmcnt(1)
	v_add_f32_e32 v36, 0, v16
	v_add_f32_e32 v16, v36, v17
	s_waitcnt lgkmcnt(0)
	v_add_f32_e32 v16, v16, v18
	v_add_f32_e32 v16, v16, v19
	v_mul_f32_e32 v16, 0x3fb8aa3b, v16
	v_exp_f32_e32 v16, v16
	s_and_saveexec_b64 s[2:3], s[6:7]
	ds_write_b32 v136, v16
	s_or_b64 exec, exec, s[2:3]
	v_cndmask_b32_e64 v36, 0, v36, s[10:11]
	v_add_f32_e32 v17, v17, v36
	v_cndmask_b32_e64 v17, v36, v17, s[12:13]
	v_add_f32_e32 v18, v18, v17
	v_cndmask_b32_e64 v17, v17, v18, s[14:15]
	v_add_f32_e32 v18, v19, v17
	v_cndmask_b32_e64 v17, v17, v18, s[16:17]
	v_add_f32_e32 v18, v20, v17
	v_mul_f32_e32 v18, 0x3fb8aa3b, v18
	v_exp_f32_e64 v36, -v18
	v_exp_f32_e32 v18, v18
	ds_read_u16 v19, v154
	ds_read_u16 v20, v154 offset:16384
	v_add_u32_e32 v187, v133, v131
	s_waitcnt lgkmcnt(1)
	v_lshlrev_b32_e32 v19, 16, v19
	s_waitcnt lgkmcnt(0)
	v_lshlrev_b32_e32 v20, 16, v20
	v_mul_f32_e32 v18, v18, v19
	v_cvt_pk_bf16_f32 v18, v18, s0
	ds_write_b16 v154, v18
	v_mul_f32_e32 v18, v36, v20
	v_cvt_pk_bf16_f32 v18, v18, s0
	ds_write_b16 v154, v18 offset:16384
	v_mul_f32_e32 v18, v16, v36
	v_mul_f32_e32 v18, v18, v20
	v_cvt_pk_bf16_f32 v18, v18, s0
	v_add_u32_e32 v19, v130, v132
	ds_write_b16 v19, v18 offset:32768
	v_add_f32_e32 v18, v21, v17
	v_mul_f32_e32 v18, 0x3fb8aa3b, v18
	v_exp_f32_e64 v21, -v18
	v_exp_f32_e32 v18, v18
	ds_read_u16 v19, v155
	ds_read_u16 v20, v155 offset:16384
	s_waitcnt lgkmcnt(1)
	v_lshlrev_b32_e32 v19, 16, v19
	s_waitcnt lgkmcnt(0)
	v_lshlrev_b32_e32 v20, 16, v20
	v_mul_f32_e32 v18, v18, v19
	v_cvt_pk_bf16_f32 v18, v18, s0
	ds_write_b16 v155, v18
	v_mul_f32_e32 v18, v21, v20
	v_cvt_pk_bf16_f32 v18, v18, s0
	ds_write_b16 v155, v18 offset:16384
	v_mul_f32_e32 v18, v16, v21
	v_mul_f32_e32 v18, v18, v20
	v_cvt_pk_bf16_f32 v18, v18, s0
	ds_write_b16 v156, v18 offset:32768
	v_add_f32_e32 v18, v22, v17
	v_mul_f32_e32 v18, 0x3fb8aa3b, v18
	v_exp_f32_e64 v21, -v18
	v_exp_f32_e32 v18, v18
	ds_read_u16 v19, v157
	ds_read_u16 v20, v157 offset:16384
	s_waitcnt lgkmcnt(1)
	v_lshlrev_b32_e32 v19, 16, v19
	s_waitcnt lgkmcnt(0)
	v_lshlrev_b32_e32 v20, 16, v20
	v_mul_f32_e32 v18, v18, v19
	v_cvt_pk_bf16_f32 v18, v18, s0
	ds_write_b16 v157, v18
	v_mul_f32_e32 v18, v21, v20
	v_cvt_pk_bf16_f32 v18, v18, s0
	ds_write_b16 v157, v18 offset:16384
	v_mul_f32_e32 v18, v16, v21
	v_mul_f32_e32 v18, v18, v20
	v_cvt_pk_bf16_f32 v18, v18, s0
	ds_write_b16 v158, v18 offset:32768
	v_add_f32_e32 v18, v23, v17
	v_mul_f32_e32 v18, 0x3fb8aa3b, v18
	v_exp_f32_e64 v21, -v18
	v_exp_f32_e32 v18, v18
	ds_read_u16 v19, v159
	ds_read_u16 v20, v159 offset:16384
	s_waitcnt lgkmcnt(1)
	v_lshlrev_b32_e32 v19, 16, v19
	s_waitcnt lgkmcnt(0)
	v_lshlrev_b32_e32 v20, 16, v20
	v_mul_f32_e32 v18, v18, v19
	v_cvt_pk_bf16_f32 v18, v18, s0
	ds_write_b16 v159, v18
	v_mul_f32_e32 v18, v21, v20
	v_cvt_pk_bf16_f32 v18, v18, s0
	ds_write_b16 v159, v18 offset:16384
	v_mul_f32_e32 v18, v16, v21
	v_mul_f32_e32 v18, v18, v20
	v_cvt_pk_bf16_f32 v18, v18, s0
	ds_write_b16 v160, v18 offset:32768
	v_add_f32_e32 v18, v24, v17
	v_mul_f32_e32 v18, 0x3fb8aa3b, v18
	v_exp_f32_e64 v21, -v18
	v_exp_f32_e32 v18, v18
	ds_read_u16 v19, v161
	ds_read_u16 v20, v161 offset:16384
	s_waitcnt lgkmcnt(1)
	v_lshlrev_b32_e32 v19, 16, v19
	s_waitcnt lgkmcnt(0)
	v_lshlrev_b32_e32 v20, 16, v20
	v_mul_f32_e32 v18, v18, v19
	v_cvt_pk_bf16_f32 v18, v18, s0
	ds_write_b16 v161, v18
	v_mul_f32_e32 v18, v21, v20
	v_cvt_pk_bf16_f32 v18, v18, s0
	ds_write_b16 v161, v18 offset:16384
	v_mul_f32_e32 v18, v16, v21
	v_mul_f32_e32 v18, v18, v20
	v_cvt_pk_bf16_f32 v18, v18, s0
	ds_write_b16 v162, v18 offset:32768
	v_add_f32_e32 v18, v25, v17
	v_mul_f32_e32 v18, 0x3fb8aa3b, v18
	v_exp_f32_e64 v21, -v18
	v_exp_f32_e32 v18, v18
	ds_read_u16 v19, v163
	ds_read_u16 v20, v163 offset:16384
	s_waitcnt lgkmcnt(1)
	v_lshlrev_b32_e32 v19, 16, v19
	s_waitcnt lgkmcnt(0)
	v_lshlrev_b32_e32 v20, 16, v20
	v_mul_f32_e32 v18, v18, v19
	v_cvt_pk_bf16_f32 v18, v18, s0
	ds_write_b16 v163, v18
	v_mul_f32_e32 v18, v21, v20
	v_cvt_pk_bf16_f32 v18, v18, s0
	ds_write_b16 v163, v18 offset:16384
	v_mul_f32_e32 v18, v16, v21
	v_mul_f32_e32 v18, v18, v20
	v_cvt_pk_bf16_f32 v18, v18, s0
	ds_write_b16 v164, v18 offset:32768
	v_add_f32_e32 v18, v26, v17
	v_mul_f32_e32 v18, 0x3fb8aa3b, v18
	v_exp_f32_e64 v21, -v18
	v_exp_f32_e32 v18, v18
	ds_read_u16 v19, v165
	ds_read_u16 v20, v165 offset:16384
	s_waitcnt lgkmcnt(1)
	v_lshlrev_b32_e32 v19, 16, v19
	s_waitcnt lgkmcnt(0)
	v_lshlrev_b32_e32 v20, 16, v20
	v_mul_f32_e32 v18, v18, v19
	v_cvt_pk_bf16_f32 v18, v18, s0
	ds_write_b16 v165, v18
	v_mul_f32_e32 v18, v21, v20
	v_cvt_pk_bf16_f32 v18, v18, s0
	ds_write_b16 v165, v18 offset:16384
	v_mul_f32_e32 v18, v16, v21
	v_mul_f32_e32 v18, v18, v20
	v_cvt_pk_bf16_f32 v18, v18, s0
	ds_write_b16 v166, v18 offset:32768
	v_add_f32_e32 v18, v27, v17
	v_mul_f32_e32 v18, 0x3fb8aa3b, v18
	v_exp_f32_e64 v21, -v18
	v_exp_f32_e32 v18, v18
	ds_read_u16 v19, v167
	ds_read_u16 v20, v167 offset:16384
	s_waitcnt lgkmcnt(1)
	v_lshlrev_b32_e32 v19, 16, v19
	s_waitcnt lgkmcnt(0)
	v_lshlrev_b32_e32 v20, 16, v20
	v_mul_f32_e32 v18, v18, v19
	v_cvt_pk_bf16_f32 v18, v18, s0
	ds_write_b16 v167, v18
	v_mul_f32_e32 v18, v21, v20
	v_cvt_pk_bf16_f32 v18, v18, s0
	ds_write_b16 v167, v18 offset:16384
	v_mul_f32_e32 v18, v16, v21
	v_mul_f32_e32 v18, v18, v20
	v_cvt_pk_bf16_f32 v18, v18, s0
	ds_write_b16 v168, v18 offset:32768
	v_add_f32_e32 v18, v28, v17
	v_mul_f32_e32 v18, 0x3fb8aa3b, v18
	v_exp_f32_e64 v21, -v18
	v_exp_f32_e32 v18, v18
	ds_read_u16 v19, v169
	ds_read_u16 v20, v169 offset:16384
	s_waitcnt lgkmcnt(1)
; DEVI u16 f2bf(float f) { return (u16)(cvtpk(f, 0.f) & 0xffffu); }
; DEVI float bf2f(u16 h) { return __uint_as_float(((unsigned)h) << 16); }
; DEVI void gla_seq(const Params& p, int l, int item, char* lds) {
;     ...
;     {
;       float pre = 0.f, tot = 0.f;
; #pragma unroll
;       for (int s_ = 0; s_ < 4; ++s_) { const float v = segtot[s_ * 128 + d]; tot += v; if (s_ < seg) pre += v; }
;       const float etot = __expf(tot);
;       if (seg == 0) ebl[d] = etot;
; #pragma unroll
;       for (int ii = 0; ii < 16; ++ii) {
;         const int i = seg * 16 + ii;
;         const float bb = bcum[ii] + pre;
;         const int so = i * 256 + (((d >> 3) ^ (i & 7)) << 4) + (d & 7) * 2;
;         const float q = bf2f(*(const u16*)(qs + so)), k = bf2f(*(const u16*)(ks + so));
;         const float eb = __expf(bb), ieb = __frcp_rn(eb);
;         *(u16*)(qs + so) = f2bf(q * eb);
;         *(u16*)(ks + so) = f2bf(k * ieb);
;         *(u16*)(kT + d * 144 + i * 2) = f2bf(k * (etot * ieb));
;       }
;     }
;     __syncthreads();
;     const char* sTc = sT + cur * 16384; char* sTn = sT + (cur ^ 1) * 16384;
;     if (wid < 4) {
	v_lshlrev_b32_e32 v19, 16, v19
	s_waitcnt lgkmcnt(0)
	v_lshlrev_b32_e32 v20, 16, v20
	v_mul_f32_e32 v18, v18, v19
	v_cvt_pk_bf16_f32 v18, v18, s0
	ds_write_b16 v169, v18
	v_mul_f32_e32 v18, v21, v20
	v_cvt_pk_bf16_f32 v18, v18, s0
	ds_write_b16 v169, v18 offset:16384
	v_mul_f32_e32 v18, v16, v21
	v_mul_f32_e32 v18, v18, v20
	v_cvt_pk_bf16_f32 v18, v18, s0
	ds_write_b16 v170, v18 offset:32768
	v_add_f32_e32 v18, v29, v17
	v_mul_f32_e32 v18, 0x3fb8aa3b, v18
	v_exp_f32_e64 v21, -v18
	v_exp_f32_e32 v18, v18
	ds_read_u16 v19, v171
	ds_read_u16 v20, v171 offset:16384
	s_waitcnt lgkmcnt(1)
	v_lshlrev_b32_e32 v19, 16, v19
	s_waitcnt lgkmcnt(0)
	v_lshlrev_b32_e32 v20, 16, v20
	v_mul_f32_e32 v18, v18, v19
	v_cvt_pk_bf16_f32 v18, v18, s0
	ds_write_b16 v171, v18
	v_mul_f32_e32 v18, v21, v20
	v_cvt_pk_bf16_f32 v18, v18, s0
	ds_write_b16 v171, v18 offset:16384
	v_mul_f32_e32 v18, v16, v21
	v_mul_f32_e32 v18, v18, v20
	v_cvt_pk_bf16_f32 v18, v18, s0
	ds_write_b16 v172, v18 offset:32768
	v_add_f32_e32 v18, v30, v17
	v_mul_f32_e32 v18, 0x3fb8aa3b, v18
	v_exp_f32_e64 v21, -v18
	v_exp_f32_e32 v18, v18
	ds_read_u16 v19, v173
	ds_read_u16 v20, v173 offset:16384
	s_waitcnt lgkmcnt(1)
	v_lshlrev_b32_e32 v19, 16, v19
	s_waitcnt lgkmcnt(0)
	v_lshlrev_b32_e32 v20, 16, v20
	v_mul_f32_e32 v18, v18, v19
	v_cvt_pk_bf16_f32 v18, v18, s0
	ds_write_b16 v173, v18
	v_mul_f32_e32 v18, v21, v20
	v_cvt_pk_bf16_f32 v18, v18, s0
	ds_write_b16 v173, v18 offset:16384
	v_mul_f32_e32 v18, v16, v21
	v_mul_f32_e32 v18, v18, v20
	v_cvt_pk_bf16_f32 v18, v18, s0
	ds_write_b16 v174, v18 offset:32768
	v_add_f32_e32 v18, v31, v17
	v_mul_f32_e32 v18, 0x3fb8aa3b, v18
	v_exp_f32_e64 v21, -v18
	v_exp_f32_e32 v18, v18
	ds_read_u16 v19, v175
	ds_read_u16 v20, v175 offset:16384
	s_waitcnt lgkmcnt(1)
	v_lshlrev_b32_e32 v19, 16, v19
	s_waitcnt lgkmcnt(0)
	v_lshlrev_b32_e32 v20, 16, v20
	v_mul_f32_e32 v18, v18, v19
	v_cvt_pk_bf16_f32 v18, v18, s0
	ds_write_b16 v175, v18
	v_mul_f32_e32 v18, v21, v20
	v_cvt_pk_bf16_f32 v18, v18, s0
	ds_write_b16 v175, v18 offset:16384
	v_mul_f32_e32 v18, v16, v21
	v_mul_f32_e32 v18, v18, v20
	v_cvt_pk_bf16_f32 v18, v18, s0
	ds_write_b16 v176, v18 offset:32768
	v_add_f32_e32 v18, v32, v17
	v_mul_f32_e32 v18, 0x3fb8aa3b, v18
	v_exp_f32_e64 v21, -v18
	v_exp_f32_e32 v18, v18
	ds_read_u16 v19, v177
	ds_read_u16 v20, v177 offset:16384
	s_waitcnt lgkmcnt(1)
	v_lshlrev_b32_e32 v19, 16, v19
	s_waitcnt lgkmcnt(0)
	v_lshlrev_b32_e32 v20, 16, v20
	v_mul_f32_e32 v18, v18, v19
	v_cvt_pk_bf16_f32 v18, v18, s0
	ds_write_b16 v177, v18
	v_mul_f32_e32 v18, v21, v20
	v_cvt_pk_bf16_f32 v18, v18, s0
	ds_write_b16 v177, v18 offset:16384
	v_mul_f32_e32 v18, v16, v21
	v_mul_f32_e32 v18, v18, v20
	v_cvt_pk_bf16_f32 v18, v18, s0
	ds_write_b16 v178, v18 offset:32768
	v_add_f32_e32 v18, v33, v17
	v_mul_f32_e32 v18, 0x3fb8aa3b, v18
	v_exp_f32_e64 v21, -v18
	v_exp_f32_e32 v18, v18
	ds_read_u16 v19, v179
	ds_read_u16 v20, v179 offset:16384
	s_waitcnt lgkmcnt(1)
	v_lshlrev_b32_e32 v19, 16, v19
	s_waitcnt lgkmcnt(0)
	v_lshlrev_b32_e32 v20, 16, v20
	v_mul_f32_e32 v18, v18, v19
	v_cvt_pk_bf16_f32 v18, v18, s0
	ds_write_b16 v179, v18
	v_mul_f32_e32 v18, v21, v20
	v_cvt_pk_bf16_f32 v18, v18, s0
	ds_write_b16 v179, v18 offset:16384
	v_mul_f32_e32 v18, v16, v21
	v_mul_f32_e32 v18, v18, v20
	v_cvt_pk_bf16_f32 v18, v18, s0
	ds_write_b16 v180, v18 offset:32768
	v_add_f32_e32 v18, v34, v17
	v_mul_f32_e32 v18, 0x3fb8aa3b, v18
	v_exp_f32_e64 v21, -v18
	v_exp_f32_e32 v18, v18
	ds_read_u16 v19, v181
	ds_read_u16 v20, v181 offset:16384
	v_add_f32_e32 v17, v35, v17
	v_mul_f32_e32 v17, 0x3fb8aa3b, v17
	s_waitcnt lgkmcnt(1)
	v_lshlrev_b32_e32 v19, 16, v19
	s_waitcnt lgkmcnt(0)
	v_lshlrev_b32_e32 v20, 16, v20
	v_exp_f32_e32 v17, v17
	v_mul_f32_e32 v18, v18, v19
	v_cvt_pk_bf16_f32 v18, v18, s0
	ds_write_b16 v181, v18
	v_mul_f32_e32 v18, v21, v20
	v_cvt_pk_bf16_f32 v18, v18, s0
	ds_write_b16 v181, v18 offset:16384
	v_mul_f32_e32 v18, v16, v21
	v_mul_f32_e32 v18, v18, v20
	v_div_scale_f32 v20, s[2:3], v17, v17, 1.0
	v_rcp_f32_e32 v21, v20
	v_cvt_pk_bf16_f32 v18, v18, s0
	ds_write_b16 v182, v18 offset:32768
	ds_read_u16 v18, v183
	ds_read_u16 v19, v183 offset:16384
	v_fma_f32 v22, -v20, v21, 1.0
	v_fmac_f32_e32 v21, v22, v21
	v_div_scale_f32 v22, vcc, 1.0, v17, 1.0
	v_mul_f32_e32 v23, v22, v21
	v_fma_f32 v24, -v20, v23, v22
	v_fmac_f32_e32 v23, v24, v21
	v_fma_f32 v20, -v20, v23, v22
	s_waitcnt lgkmcnt(1)
	v_lshlrev_b32_e32 v18, 16, v18
	v_div_fmas_f32 v20, v20, v21, v23
	v_div_fixup_f32 v20, v20, v17, 1.0
	v_mul_f32_e32 v17, v17, v18
	s_waitcnt lgkmcnt(0)
	v_lshlrev_b32_e32 v19, 16, v19
	v_cvt_pk_bf16_f32 v17, v17, s0
	v_mul_f32_e32 v16, v16, v20
	ds_write_b16 v183, v17
	v_mul_f32_e32 v17, v20, v19
	v_mul_f32_e32 v16, v16, v19
	v_cvt_pk_bf16_f32 v17, v17, s0
	v_cvt_pk_bf16_f32 v16, v16, s0
	ds_write_b16 v183, v17 offset:16384
	ds_write_b16 v184, v16 offset:32768
	s_waitcnt lgkmcnt(0)
	s_barrier
	s_and_saveexec_b64 s[2:3], s[8:9]
	s_cbranch_execz .LBB0_396
; DEVI int crow(int r, int hi) { return (r & 3) + 8 * (r >> 2) + 4 * hi; }
; DEVI void gla_seq(const Params& p, int l, int item, char* lds) {
;     ...
;     if (wid < 4) {
;       f32x16 p0, p1, o;
; #pragma unroll
;       for (int r = 0; r < 16; ++r) { p0[r] = 0.f; p1[r] = 0.f; o[r] = 0.f; }
;       const int irow = iblk * 32 + r32;
; #pragma unroll
;       for (int d0 = 0; d0 < 8; ++d0) {
;         const int chn = d0 * 2 + hi;
;         const bf16x8 b0 = *(const bf16x8*)(ks + r32 * 256 + ((chn ^ (r32 & 7)) << 4));
;         const bf16x8 b1 = *(const bf16x8*)(ks + (32 + r32) * 256 + ((chn ^ (r32 & 7)) << 4));
;         const bf16x8 qf = *(const bf16x8*)(qs + irow * 256 + ((chn ^ (irow & 7)) << 4));
;         p0 = __builtin_amdgcn_mfma_f32_32x32x16_bf16(b0, qf, p0, 0, 0, 0);
;         p1 = __builtin_amdgcn_mfma_f32_32x32x16_bf16(b1, qf, p1, 0, 0, 0);
;       }
; #pragma unroll
;       for (int r = 0; r < 16; ++r) {
;         const int j0 = crow(r, hi), j1 = 32 + j0;
;         const bool k0 = dir ? (j0 < irow) : (j0 <= irow), k1 = dir ? (j1 < irow) : (j1 <= irow);
;         p0[r] = k0 ? p0[r] : 0.f; p1[r] = k1 ? p1[r] : 0.f;
;       }
;       bf16x8 pa0, pa1, pa2, pa3;
;       PK4(p0, 0, pa0); PK4(p0, 8, pa1); PK4(p1, 0, pa2); PK4(p1, 8, pa3);
;       const char* vrow = vT + (eblk * 32 + r32) * 144 + hi * 16;
;       o = __builtin_amdgcn_mfma_f32_32x32x16_bf16(pa0, *(const bf16x8*)(vrow), o, 0, 0, 0);
;       o = __builtin_amdgcn_mfma_f32_32x32x16_bf16(pa1, *(const bf16x8*)(vrow + 32), o, 0, 0, 0);
;       o = __builtin_amdgcn_mfma_f32_32x32x16_bf16(pa2, *(const bf16x8*)(vrow + 64), o, 0, 0, 0);
;       o = __builtin_amdgcn_mfma_f32_32x32x16_bf16(pa3, *(const bf16x8*)(vrow + 96), o, 0, 0, 0);
	v_add_u32_e32 v32, v137, v139
	ds_read_b128 v[16:19], v32 offset:16384
	v_add_u32_e32 v20, v138, v139
	ds_read_b128 v[68:71], v20
	v_add_u32_e32 v80, v137, v140
	ds_read_b128 v[76:79], v80 offset:16384
	ds_read_b128 v[32:35], v32 offset:24576
	v_add_u32_e32 v72, v138, v140
	ds_read_b128 v[72:75], v72
	v_add_u32_e32 v84, v137, v141
	s_waitcnt lgkmcnt(3)
	v_mfma_f32_32x32x16_bf16 v[16:31], v[16:19], v[68:71], 0
	v_add_u32_e32 v88, v137, v142
	v_add_u32_e32 v92, v137, v143
	v_add_u32_e32 v96, v137, v144
	v_add_u32_e32 v188, v137, v145
	v_add_u32_e32 v194, v137, v146
	v_readlane_b32 s68, v254, 30
	v_readlane_b32 s69, v254, 31
	s_waitcnt lgkmcnt(0)
	v_mfma_f32_32x32x16_bf16 v[16:31], v[76:79], v[72:75], v[16:31]
	ds_read_b128 v[76:79], v80 offset:24576
	ds_read_b128 v[80:83], v84 offset:16384
	s_add_i32 s27, s93, 0xffffff00
	s_cmp_lt_u32 s46, 4
	s_cselect_b32 s27, s93, s27
	s_cselect_b32 s29, 0x2000, 0
	v_mfma_f32_32x32x16_bf16 v[32:47], v[32:35], v[68:71], 0
	s_waitcnt lgkmcnt(1)
	v_mfma_f32_32x32x16_bf16 v[32:47], v[76:79], v[72:75], v[32:47]
	v_add_u32_e32 v76, v138, v141
	ds_read_b128 v[76:79], v76
	s_waitcnt lgkmcnt(0)
	v_mfma_f32_32x32x16_bf16 v[16:31], v[80:83], v[76:79], v[16:31]
	ds_read_b128 v[80:83], v84 offset:24576
	ds_read_b128 v[84:87], v88 offset:16384
	s_waitcnt lgkmcnt(1)
	v_mfma_f32_32x32x16_bf16 v[32:47], v[80:83], v[76:79], v[32:47]
	v_add_u32_e32 v80, v138, v142
	ds_read_b128 v[80:83], v80
	s_waitcnt lgkmcnt(0)
	v_mfma_f32_32x32x16_bf16 v[16:31], v[84:87], v[80:83], v[16:31]
	ds_read_b128 v[84:87], v88 offset:24576
	ds_read_b128 v[88:91], v92 offset:16384
	s_waitcnt lgkmcnt(1)
	v_mfma_f32_32x32x16_bf16 v[32:47], v[84:87], v[80:83], v[32:47]
	v_add_u32_e32 v84, v138, v143
	ds_read_b128 v[84:87], v84
	s_waitcnt lgkmcnt(0)
	v_mfma_f32_32x32x16_bf16 v[16:31], v[88:91], v[84:87], v[16:31]
	ds_read_b128 v[88:91], v92 offset:24576
	ds_read_b128 v[92:95], v96 offset:16384
	s_waitcnt lgkmcnt(1)
	v_mfma_f32_32x32x16_bf16 v[32:47], v[88:91], v[84:87], v[32:47]
	v_add_u32_e32 v88, v138, v144
	ds_read_b128 v[88:91], v88
	s_waitcnt lgkmcnt(0)
	v_mfma_f32_32x32x16_bf16 v[16:31], v[92:95], v[88:91], v[16:31]
	ds_read_b128 v[92:95], v96 offset:24576
	ds_read_b128 v[96:99], v188 offset:16384
	s_waitcnt lgkmcnt(1)
	v_mfma_f32_32x32x16_bf16 v[32:47], v[92:95], v[88:91], v[32:47]
	v_add_u32_e32 v92, v138, v145
	ds_read_b128 v[92:95], v92
	s_waitcnt lgkmcnt(0)
	v_mfma_f32_32x32x16_bf16 v[16:31], v[96:99], v[92:95], v[16:31]
	ds_read_b128 v[96:99], v188 offset:24576
	ds_read_b128 v[188:191], v194 offset:16384
	s_waitcnt lgkmcnt(1)
	v_mfma_f32_32x32x16_bf16 v[32:47], v[96:99], v[92:95], v[32:47]
	v_add_u32_e32 v96, v138, v146
	ds_read_b128 v[96:99], v96
	s_waitcnt lgkmcnt(0)
	v_mfma_f32_32x32x16_bf16 v[16:31], v[188:191], v[96:99], v[16:31]
	ds_read_b128 v[188:191], v194 offset:24576
	s_waitcnt lgkmcnt(0)
	v_mfma_f32_32x32x16_bf16 v[32:47], v[188:191], v[96:99], v[32:47]
	s_nop 8
	v_cndmask_b32_e64 v16, 0, v16, s[72:73]
	v_cndmask_b32_e64 v27, 0, v27, s[50:51]
	v_cndmask_b32_e64 v28, 0, v28, s[38:39]
	v_cndmask_b32_e64 v29, 0, v29, s[42:43]
	v_cndmask_b32_e64 v30, 0, v30, s[76:77]
	v_cndmask_b32_e64 v31, 0, v31, s[80:81]
	v_cndmask_b32_e64 v188, 0, v32, s[68:69]
	v_readlane_b32 s68, v254, 32
	v_readlane_b32 s69, v254, 33
	v_cndmask_b32_e64 v199, 0, v42, s[48:49]
	v_cndmask_b32_e64 v200, 0, v43, s[30:31]
	v_cndmask_b32_e64 v17, 0, v17, s[68:69]
	v_readlane_b32 s68, v254, 34
	v_readlane_b32 s69, v254, 35
	v_cvt_pk_bf16_f32 v16, v16, v17
	v_cndmask_b32_e64 v44, 0, v44, s[40:41]
	v_cndmask_b32_e64 v189, 0, v33, s[68:69]
	v_readlane_b32 s68, v254, 36
	v_readlane_b32 s69, v254, 37
	v_cndmask_b32_e64 v45, 0, v45, s[44:45]
	v_cndmask_b32_e64 v46, 0, v46, s[78:79]
	v_cndmask_b32_e64 v18, 0, v18, s[68:69]
	v_readlane_b32 s68, v254, 38
	v_readlane_b32 s69, v254, 39
	v_cndmask_b32_e64 v47, 0, v47, s[82:83]
	s_nop 0
	v_cndmask_b32_e64 v190, 0, v34, s[68:69]
	v_readlane_b32 s68, v254, 40
	v_readlane_b32 s69, v254, 41
	v_cvt_pk_bf16_f32 v34, v28, v29
	s_nop 0
	v_cndmask_b32_e64 v19, 0, v19, s[68:69]
	v_readlane_b32 s68, v254, 42
	v_readlane_b32 s69, v254, 43
	v_cvt_pk_bf16_f32 v17, v18, v19
	s_nop 0
	v_cndmask_b32_e64 v191, 0, v35, s[68:69]
	v_readlane_b32 s68, v254, 44
	v_readlane_b32 s69, v254, 45
	v_cvt_pk_bf16_f32 v35, v30, v31
	s_nop 0
	v_cndmask_b32_e64 v20, 0, v20, s[68:69]
	v_readlane_b32 s68, v254, 46
	v_readlane_b32 s69, v254, 47
	s_nop 1
	v_cndmask_b32_e64 v194, 0, v36, s[68:69]
	v_readlane_b32 s68, v254, 48
	v_readlane_b32 s69, v254, 49
	v_cvt_pk_bf16_f32 v36, v188, v189
	s_nop 0
	v_cndmask_b32_e64 v21, 0, v21, s[68:69]
	v_readlane_b32 s68, v254, 50
	v_readlane_b32 s69, v254, 51
	v_cvt_pk_bf16_f32 v18, v20, v21
	s_nop 1
	v_permlane32_swap_b32_e32 v16, v18
	v_cndmask_b32_e64 v195, 0, v37, s[68:69]
	v_readlane_b32 s68, v254, 52
	v_readlane_b32 s69, v254, 53
	v_cvt_pk_bf16_f32 v37, v190, v191
	s_nop 0
	v_cndmask_b32_e64 v22, 0, v22, s[68:69]
	v_readlane_b32 s68, v254, 54
	v_readlane_b32 s69, v254, 55
	s_nop 1
	v_cndmask_b32_e64 v196, 0, v38, s[68:69]
	v_readlane_b32 s68, v254, 56
	v_readlane_b32 s69, v254, 57
	v_cvt_pk_bf16_f32 v38, v194, v195
	s_nop 1
	v_permlane32_swap_b32_e32 v36, v38
	v_cndmask_b32_e64 v23, 0, v23, s[68:69]
	v_readlane_b32 s68, v254, 58
	v_readlane_b32 s69, v254, 59
	v_cvt_pk_bf16_f32 v19, v22, v23
	s_nop 1
	v_permlane32_swap_b32_e32 v17, v19
	v_cndmask_b32_e64 v39, 0, v39, s[68:69]
	v_readlane_b32 s68, v254, 60
	v_readlane_b32 s69, v254, 61
	ds_read_b128 v[20:23], v187 offset:51200
	v_cvt_pk_bf16_f32 v39, v196, v39
	v_cndmask_b32_e64 v24, 0, v24, s[68:69]
	v_readlane_b32 s68, v254, 62
	v_readlane_b32 s69, v254, 63
	v_permlane32_swap_b32_e32 v37, v39
	s_nop 0
	v_cndmask_b32_e64 v197, 0, v40, s[68:69]
	v_readlane_b32 s68, v255, 0
	v_readlane_b32 s69, v255, 1
	s_nop 1
	v_cndmask_b32_e64 v25, 0, v25, s[68:69]
	v_readlane_b32 s68, v255, 2
	v_readlane_b32 s69, v255, 3
	v_cvt_pk_bf16_f32 v32, v24, v25
	s_nop 1
	v_permlane32_swap_b32_e32 v32, v34
	v_cndmask_b32_e64 v198, 0, v41, s[68:69]
	v_readlane_b32 s68, v255, 4
	v_readlane_b32 s69, v255, 5
	ds_read_b128 v[40:43], v187 offset:51232
	s_nop 0
	v_cndmask_b32_e64 v26, 0, v26, s[68:69]
	v_cvt_pk_bf16_f32 v33, v26, v27
	s_waitcnt lgkmcnt(1)
; DEVI u16 f2bf(float f) { return (u16)(cvtpk(f, 0.f) & 0xffffu); }
; DEVI int crow(int r, int hi) { return (r & 3) + 8 * (r >> 2) + 4 * hi; }
; DEVI void gla_seq(const Params& p, int l, int item, char* lds) {
;     ...
;       const char* vrow = vT + (eblk * 32 + r32) * 144 + hi * 16;
;       o = __builtin_amdgcn_mfma_f32_32x32x16_bf16(pa0, *(const bf16x8*)(vrow), o, 0, 0, 0);
;       o = __builtin_amdgcn_mfma_f32_32x32x16_bf16(pa1, *(const bf16x8*)(vrow + 32), o, 0, 0, 0);
;       o = __builtin_amdgcn_mfma_f32_32x32x16_bf16(pa2, *(const bf16x8*)(vrow + 64), o, 0, 0, 0);
;       o = __builtin_amdgcn_mfma_f32_32x32x16_bf16(pa3, *(const bf16x8*)(vrow + 96), o, 0, 0, 0);
;       const int erow = eblk * 32 + r32;
; #pragma unroll
;       for (int d0 = 0; d0 < 8; ++d0) {
;         const int chn = d0 * 2 + hi;
;         const bf16x8 qf = *(const bf16x8*)(qs + irow * 256 + ((chn ^ (irow & 7)) << 4));
;         const bf16x8 sf = *(const bf16x8*)(sTc + erow * 256 + ((chn ^ (erow & 7)) << 4));
;         o = __builtin_amdgcn_mfma_f32_32x32x16_bf16(qf, sf, o, 0, 0, 0);
;       }
; #pragma unroll
;       for (int r = 0; r < 16; ++r)
;         og[gla_row(bi, dir, cc, iblk * 32 + crow(r, hi)) * 1024 + h * 256 + sl * 64 + eblk * 32 + r32] = f2bf(o[r]);
	v_mfma_f32_32x32x16_bf16 v[16:31], v[16:19], v[20:23], 0
	v_permlane32_swap_b32_e32 v33, v35
	v_readlane_b32 s68, v253, 21
	s_waitcnt lgkmcnt(0)
	v_mfma_f32_32x32x16_bf16 v[16:31], v[32:35], v[40:43], v[16:31]
	ds_read_b128 v[40:43], v187 offset:51264
	v_cvt_pk_bf16_f32 v32, v197, v198
	v_cvt_pk_bf16_f32 v33, v199, v200
	v_cvt_pk_bf16_f32 v34, v44, v45
	v_cvt_pk_bf16_f32 v35, v46, v47
	s_nop 0
	v_permlane32_swap_b32_e32 v32, v34
	s_waitcnt lgkmcnt(0)
	v_mfma_f32_32x32x16_bf16 v[16:31], v[36:39], v[40:43], v[16:31]
	v_permlane32_swap_b32_e32 v33, v35
	ds_read_b128 v[36:39], v187 offset:51296
	s_waitcnt lgkmcnt(0)
	v_mfma_f32_32x32x16_bf16 v[16:31], v[32:35], v[36:39], v[16:31]
	v_lshl_add_u32 v36, s75, 14, v134
	v_add_u32_e32 v32, v36, v139
	ds_read_b128 v[32:35], v32 offset:60416
	s_waitcnt lgkmcnt(0)
	v_mfma_f32_32x32x16_bf16 v[16:31], v[68:71], v[32:35], v[16:31]
	v_add_u32_e32 v32, v36, v140
	ds_read_b128 v[32:35], v32 offset:60416
	s_waitcnt lgkmcnt(0)
	v_mfma_f32_32x32x16_bf16 v[16:31], v[72:75], v[32:35], v[16:31]
	v_add_u32_e32 v32, v36, v141
	ds_read_b128 v[32:35], v32 offset:60416
	s_waitcnt lgkmcnt(0)
	v_mfma_f32_32x32x16_bf16 v[16:31], v[76:79], v[32:35], v[16:31]
	v_add_u32_e32 v32, v36, v142
	ds_read_b128 v[32:35], v32 offset:60416
	s_waitcnt lgkmcnt(0)
	v_mfma_f32_32x32x16_bf16 v[16:31], v[80:83], v[32:35], v[16:31]
	v_add_u32_e32 v32, v36, v143
	ds_read_b128 v[32:35], v32 offset:60416
	s_waitcnt lgkmcnt(0)
	v_mfma_f32_32x32x16_bf16 v[16:31], v[84:87], v[32:35], v[16:31]
	v_add_u32_e32 v32, v36, v144
	ds_read_b128 v[32:35], v32 offset:60416
	s_waitcnt lgkmcnt(0)
	v_mfma_f32_32x32x16_bf16 v[16:31], v[88:91], v[32:35], v[16:31]
	v_add_u32_e32 v32, v36, v145
	ds_read_b128 v[32:35], v32 offset:60416
	v_add_u32_e32 v36, v36, v146
	ds_read_b128 v[36:39], v36 offset:60416
	s_waitcnt lgkmcnt(1)
	v_mfma_f32_32x32x16_bf16 v[16:31], v[92:95], v[32:35], v[16:31]
	v_or_b32_e32 v34, s27, v151
	s_cselect_b32 s27, 0xff, s61
	v_sub_u32_e32 v32, s27, v34
	s_add_i32 s29, s29, s68
	v_cndmask_b32_e64 v32, v32, v34, s[4:5]
	v_add_u32_e32 v32, s29, v32
	v_ashrrev_i32_e32 v33, 31, v32
	s_waitcnt lgkmcnt(0)
; DEVI u16 f2bf(float f) { return (u16)(cvtpk(f, 0.f) & 0xffffu); }
; DEVI int crow(int r, int hi) { return (r & 3) + 8 * (r >> 2) + 4 * hi; }
; DEVI long gla_row(int bi, int dir, int cc, int i) {
;   const int L = (cc < 4) ? CTXL : SEQ, c = (cc < 4) ? cc : cc - 4, rb = bi * ROWS + ((cc < 4) ? SEQ : 0);
;   const int tl = c * 64 + i;
;   return (long)(rb + (dir ? (L - 1 - tl) : tl));
; }
; DEVI void gla_seq(const Params& p, int l, int item, char* lds) {
;     ...
; #pragma unroll
;       for (int r = 0; r < 16; ++r)
;         og[gla_row(bi, dir, cc, iblk * 32 + crow(r, hi)) * 1024 + h * 256 + sl * 64 + eblk * 32 + r32] = f2bf(o[r]);
	v_mfma_f32_32x32x16_bf16 v[16:31], v[96:99], v[36:39], v[16:31]
	v_lshlrev_b64 v[32:33], 11, v[32:33]
	v_lshl_add_u64 v[32:33], v[102:103], 0, v[32:33]
	s_nop 9
	v_cvt_pk_bf16_f32 v16, v16, s0
	global_store_short v[32:33], v16, off
	v_or_b32_e32 v16, 1, v34
	v_cvt_pk_bf16_f32 v32, v17, s0
	v_sub_u32_e32 v17, s27, v16
	v_cndmask_b32_e64 v16, v17, v16, s[4:5]
	v_add_u32_e32 v16, s29, v16
	v_ashrrev_i32_e32 v17, 31, v16
	v_lshlrev_b64 v[16:17], 11, v[16:17]
	v_lshl_add_u64 v[16:17], v[102:103], 0, v[16:17]
	global_store_short v[16:17], v32, off
	v_or_b32_e32 v16, 2, v34
	v_sub_u32_e32 v17, s27, v16
	v_cndmask_b32_e64 v16, v17, v16, s[4:5]
	v_add_u32_e32 v16, s29, v16
	v_ashrrev_i32_e32 v17, 31, v16
	v_lshlrev_b64 v[16:17], 11, v[16:17]
	v_cvt_pk_bf16_f32 v18, v18, s0
	v_lshl_add_u64 v[16:17], v[102:103], 0, v[16:17]
	global_store_short v[16:17], v18, off
	v_or_b32_e32 v16, 3, v34
	v_sub_u32_e32 v17, s27, v16
	v_cndmask_b32_e64 v16, v17, v16, s[4:5]
	v_add_u32_e32 v16, s29, v16
	v_ashrrev_i32_e32 v17, 31, v16
	v_lshlrev_b64 v[16:17], 11, v[16:17]
	v_cvt_pk_bf16_f32 v18, v19, s0
	v_lshl_add_u64 v[16:17], v[102:103], 0, v[16:17]
	global_store_short v[16:17], v18, off
	v_or_b32_e32 v16, 8, v34
	v_sub_u32_e32 v17, s27, v16
	v_cndmask_b32_e64 v16, v17, v16, s[4:5]
	v_add_u32_e32 v16, s29, v16
	v_ashrrev_i32_e32 v17, 31, v16
	v_lshlrev_b64 v[16:17], 11, v[16:17]
	v_cvt_pk_bf16_f32 v18, v20, s0
	v_lshl_add_u64 v[16:17], v[102:103], 0, v[16:17]
	global_store_short v[16:17], v18, off
	v_or_b32_e32 v16, 9, v34
	v_sub_u32_e32 v17, s27, v16
	v_cndmask_b32_e64 v16, v17, v16, s[4:5]
	v_add_u32_e32 v16, s29, v16
	v_ashrrev_i32_e32 v17, 31, v16
	v_lshlrev_b64 v[16:17], 11, v[16:17]
	v_cvt_pk_bf16_f32 v18, v21, s0
	v_lshl_add_u64 v[16:17], v[102:103], 0, v[16:17]
	global_store_short v[16:17], v18, off
	v_or_b32_e32 v16, 10, v34
	v_sub_u32_e32 v17, s27, v16
	v_cndmask_b32_e64 v16, v17, v16, s[4:5]
	v_add_u32_e32 v16, s29, v16
	v_ashrrev_i32_e32 v17, 31, v16
	v_lshlrev_b64 v[16:17], 11, v[16:17]
	v_cvt_pk_bf16_f32 v18, v22, s0
	v_lshl_add_u64 v[16:17], v[102:103], 0, v[16:17]
	global_store_short v[16:17], v18, off
	v_or_b32_e32 v16, 11, v34
	v_sub_u32_e32 v17, s27, v16
	v_cndmask_b32_e64 v16, v17, v16, s[4:5]
	v_add_u32_e32 v16, s29, v16
	v_ashrrev_i32_e32 v17, 31, v16
	v_lshlrev_b64 v[16:17], 11, v[16:17]
	v_cvt_pk_bf16_f32 v18, v23, s0
	v_lshl_add_u64 v[16:17], v[102:103], 0, v[16:17]
	global_store_short v[16:17], v18, off
	v_or_b32_e32 v16, 16, v34
	v_sub_u32_e32 v17, s27, v16
	v_cndmask_b32_e64 v16, v17, v16, s[4:5]
	v_add_u32_e32 v16, s29, v16
	v_ashrrev_i32_e32 v17, 31, v16
	v_lshlrev_b64 v[16:17], 11, v[16:17]
	v_cvt_pk_bf16_f32 v18, v24, s0
	v_lshl_add_u64 v[16:17], v[102:103], 0, v[16:17]
	global_store_short v[16:17], v18, off
	v_or_b32_e32 v16, 17, v34
	v_sub_u32_e32 v17, s27, v16
	v_cndmask_b32_e64 v16, v17, v16, s[4:5]
	v_add_u32_e32 v16, s29, v16
	v_ashrrev_i32_e32 v17, 31, v16
	v_lshlrev_b64 v[16:17], 11, v[16:17]
	v_cvt_pk_bf16_f32 v18, v25, s0
	v_lshl_add_u64 v[16:17], v[102:103], 0, v[16:17]
	global_store_short v[16:17], v18, off
	v_or_b32_e32 v16, 18, v34
	v_sub_u32_e32 v17, s27, v16
	v_cndmask_b32_e64 v16, v17, v16, s[4:5]
	v_add_u32_e32 v16, s29, v16
	v_ashrrev_i32_e32 v17, 31, v16
	v_lshlrev_b64 v[16:17], 11, v[16:17]
	v_cvt_pk_bf16_f32 v18, v26, s0
	v_lshl_add_u64 v[16:17], v[102:103], 0, v[16:17]
	global_store_short v[16:17], v18, off
	v_or_b32_e32 v16, 19, v34
	v_sub_u32_e32 v17, s27, v16
	v_cndmask_b32_e64 v16, v17, v16, s[4:5]
	v_add_u32_e32 v16, s29, v16
	v_ashrrev_i32_e32 v17, 31, v16
	v_lshlrev_b64 v[16:17], 11, v[16:17]
	v_cvt_pk_bf16_f32 v18, v27, s0
	v_lshl_add_u64 v[16:17], v[102:103], 0, v[16:17]
	global_store_short v[16:17], v18, off
	v_or_b32_e32 v16, 24, v34
	v_sub_u32_e32 v17, s27, v16
	v_cndmask_b32_e64 v16, v17, v16, s[4:5]
	v_add_u32_e32 v16, s29, v16
	v_ashrrev_i32_e32 v17, 31, v16
	v_lshlrev_b64 v[16:17], 11, v[16:17]
	v_cvt_pk_bf16_f32 v18, v28, s0
	v_lshl_add_u64 v[16:17], v[102:103], 0, v[16:17]
	global_store_short v[16:17], v18, off
	v_or_b32_e32 v16, 25, v34
	v_sub_u32_e32 v17, s27, v16
	v_cndmask_b32_e64 v16, v17, v16, s[4:5]
	v_add_u32_e32 v16, s29, v16
	v_ashrrev_i32_e32 v17, 31, v16
	v_lshlrev_b64 v[16:17], 11, v[16:17]
	v_cvt_pk_bf16_f32 v18, v29, s0
	v_lshl_add_u64 v[16:17], v[102:103], 0, v[16:17]
	global_store_short v[16:17], v18, off
	v_or_b32_e32 v16, 26, v34
	v_sub_u32_e32 v17, s27, v16
	v_cndmask_b32_e64 v16, v17, v16, s[4:5]
	v_add_u32_e32 v16, s29, v16
	v_ashrrev_i32_e32 v17, 31, v16
	v_lshlrev_b64 v[16:17], 11, v[16:17]
	v_cvt_pk_bf16_f32 v18, v30, s0
	v_lshl_add_u64 v[16:17], v[102:103], 0, v[16:17]
	global_store_short v[16:17], v18, off
	v_or_b32_e32 v16, 27, v34
	v_sub_u32_e32 v17, s27, v16
	v_cndmask_b32_e64 v16, v17, v16, s[4:5]
	v_add_u32_e32 v16, s29, v16
	v_ashrrev_i32_e32 v17, 31, v16
	v_lshlrev_b64 v[16:17], 11, v[16:17]
	v_cvt_pk_bf16_f32 v18, v31, s0
	v_lshl_add_u64 v[16:17], v[102:103], 0, v[16:17]
	global_store_short v[16:17], v18, off
	s_branch .LBB0_396
